# phase B2 k-step software pipelined: next k-step partial-sum and weight loads issued during current silu/MFMA
# baseline (speedup 1.0000x reference)
; DI unsigned pk2(float lo, float hi) { f32x2 v = {lo, hi}; bf16x2_t b = __builtin_convertvector(v, bf16x2_t); return __builtin_bit_cast(unsigned, b); }
; DI float siluf_(float x) { return x * __builtin_amdgcn_rcpf(1.f + __builtin_amdgcn_exp2f(-1.44269504089f * x)); }
; DI void phaseB2(const Params& p0, int layer, unsigned char* lds) {
;     ...
;     for (int ksx = 0; ksx < 8; ++ksx) {
;       f32x4 h0 = *(const f32x4*)(bias_s + kv * 256 + ksx * 32 + quad * 8), h1 = *(const f32x4*)(bias_s + kv * 256 + ksx * 32 + quad * 8 + 4);
; #pragma unroll
;       for (int sp = 0; sp < 4; ++sp) { const float* q = hp + (long)sp * 32 * 256 * 256 + ksx * 32; h0 += *(const f32x4*)q; h1 += *(const f32x4*)(q + 4); }
;       const bf16x8 hf = mk8((u32x4){pk2(siluf_(h0[0]), siluf_(h0[1])), pk2(siluf_(h0[2]), siluf_(h0[3])), pk2(siluf_(h1[0]), siluf_(h1[1])), pk2(siluf_(h1[2]), siluf_(h1[3]))});
.LBB0_630:
	s_cmp_lg_u32 s27, 0
	s_cbranch_scc1 .Lmy_b2_steady
	v_lshl_add_u64 v[42:43], v[38:39], 0, s[4:5]
	s_mov_b64 s[28:29], 0x1d570000
	v_lshl_add_u64 v[56:57], v[42:43], 0, s[28:29]
	global_load_dwordx4 v[60:63], v[56:57], off
	global_load_dwordx4 v[64:67], v[56:57], off offset:16
	s_mov_b64 s[28:29], 0x1dd70000
	v_lshl_add_u64 v[56:57], v[42:43], 0, s[28:29]
	global_load_dwordx4 v[68:71], v[56:57], off
	global_load_dwordx4 v[72:75], v[56:57], off offset:16
	s_mov_b64 s[28:29], 0x1e570000
	v_lshl_add_u64 v[56:57], v[42:43], 0, s[28:29]
	global_load_dwordx4 v[76:79], v[56:57], off
	global_load_dwordx4 v[80:83], v[56:57], off offset:16
	s_mov_b64 s[28:29], 0x1ed70000
	v_lshl_add_u64 v[56:57], v[42:43], 0, s[28:29]
	global_load_dwordx4 v[84:87], v[56:57], off
	global_load_dwordx4 v[88:91], v[56:57], off offset:16
	v_lshl_add_u64 v[42:43], v[40:41], 0, s[4:5]
	s_mov_b64 s[28:29], 0xec0000
	v_lshl_add_u64 v[56:57], v[42:43], 0, s[28:29]
	global_load_dwordx4 v[100:103], v[56:57], off
	s_mov_b64 s[28:29], 0xec2000
	v_lshl_add_u64 v[56:57], v[42:43], 0, s[28:29]
	global_load_dwordx4 v[104:107], v[56:57], off
	s_mov_b64 s[28:29], 0xec4000
	v_lshl_add_u64 v[56:57], v[42:43], 0, s[28:29]
	global_load_dwordx4 v[108:111], v[56:57], off
	s_mov_b64 s[28:29], 0xec6000
	v_lshl_add_u64 v[56:57], v[42:43], 0, s[28:29]
	global_load_dwordx4 v[112:115], v[56:57], off
.Lmy_b2_steady:
	v_add_u32_e32 v0, s27, v37
	ds_read_b128 v[92:95], v0
	ds_read_b128 v[96:99], v0 offset:16
	s_waitcnt vmcnt(10) lgkmcnt(0)
	v_pk_add_f32 v[92:93], v[92:93], v[60:61]
	v_pk_add_f32 v[94:95], v[94:95], v[62:63]
	v_pk_add_f32 v[96:97], v[96:97], v[64:65]
	v_pk_add_f32 v[98:99], v[98:99], v[66:67]
	s_waitcnt vmcnt(8)
	v_pk_add_f32 v[92:93], v[92:93], v[68:69]
	v_pk_add_f32 v[94:95], v[94:95], v[70:71]
	v_pk_add_f32 v[96:97], v[96:97], v[72:73]
	v_pk_add_f32 v[98:99], v[98:99], v[74:75]
	s_waitcnt vmcnt(6)
	v_pk_add_f32 v[92:93], v[92:93], v[76:77]
	v_pk_add_f32 v[94:95], v[94:95], v[78:79]
	v_pk_add_f32 v[96:97], v[96:97], v[80:81]
	v_pk_add_f32 v[98:99], v[98:99], v[82:83]
	s_waitcnt vmcnt(4)
	v_pk_add_f32 v[92:93], v[92:93], v[84:85]
	v_pk_add_f32 v[94:95], v[94:95], v[86:87]
	v_pk_add_f32 v[96:97], v[96:97], v[88:89]
	v_pk_add_f32 v[98:99], v[98:99], v[90:91]
	s_cmpk_eq_i32 s27, 0x380
	s_cbranch_scc1 .Lmy_b2_last
	v_lshl_add_u64 v[42:43], v[38:39], 0, s[6:7]
	v_lshl_add_u64 v[42:43], v[42:43], 0, s[4:5]
	s_mov_b64 s[28:29], 0x1d570000
	v_lshl_add_u64 v[56:57], v[42:43], 0, s[28:29]
	global_load_dwordx4 v[60:63], v[56:57], off
	global_load_dwordx4 v[64:67], v[56:57], off offset:16
	s_mov_b64 s[28:29], 0x1dd70000
	v_lshl_add_u64 v[56:57], v[42:43], 0, s[28:29]
	global_load_dwordx4 v[68:71], v[56:57], off
	global_load_dwordx4 v[72:75], v[56:57], off offset:16
	s_mov_b64 s[28:29], 0x1e570000
	v_lshl_add_u64 v[56:57], v[42:43], 0, s[28:29]
	global_load_dwordx4 v[76:79], v[56:57], off
	global_load_dwordx4 v[80:83], v[56:57], off offset:16
	s_mov_b64 s[28:29], 0x1ed70000
	v_lshl_add_u64 v[56:57], v[42:43], 0, s[28:29]
	global_load_dwordx4 v[84:87], v[56:57], off
	global_load_dwordx4 v[88:91], v[56:57], off offset:16
.Lmy_b2_last:
	v_mul_f32_e32 v116, 0xbfb8aa3b, v92
	v_mul_f32_e32 v117, 0xbfb8aa3b, v93
	v_mul_f32_e32 v118, 0xbfb8aa3b, v94
	v_mul_f32_e32 v119, 0xbfb8aa3b, v95
	v_mul_f32_e32 v120, 0xbfb8aa3b, v96
	v_mul_f32_e32 v121, 0xbfb8aa3b, v97
	v_mul_f32_e32 v122, 0xbfb8aa3b, v98
	v_mul_f32_e32 v123, 0xbfb8aa3b, v99
	v_exp_f32_e32 v116, v116
	v_exp_f32_e32 v117, v117
	v_exp_f32_e32 v118, v118
	v_exp_f32_e32 v119, v119
	v_exp_f32_e32 v120, v120
	v_exp_f32_e32 v121, v121
	v_exp_f32_e32 v122, v122
	v_exp_f32_e32 v123, v123
	v_add_f32_e32 v116, 1.0, v116
	v_add_f32_e32 v117, 1.0, v117
	v_add_f32_e32 v118, 1.0, v118
	v_add_f32_e32 v119, 1.0, v119
	v_add_f32_e32 v120, 1.0, v120
	v_add_f32_e32 v121, 1.0, v121
	v_add_f32_e32 v122, 1.0, v122
	v_add_f32_e32 v123, 1.0, v123
	v_rcp_f32_e32 v124, v116
	v_rcp_f32_e32 v125, v117
	v_rcp_f32_e32 v126, v118
	v_rcp_f32_e32 v127, v119
	v_rcp_f32_e32 v128, v120
	v_rcp_f32_e32 v129, v121
	v_rcp_f32_e32 v130, v122
	v_rcp_f32_e32 v131, v123
	v_pk_mul_f32 v[92:93], v[92:93], v[124:125]
	v_pk_mul_f32 v[94:95], v[94:95], v[126:127]
	v_pk_mul_f32 v[96:97], v[96:97], v[128:129]
	v_pk_mul_f32 v[98:99], v[98:99], v[130:131]
	v_cvt_pk_bf16_f32 v18, v92, v93
	v_cvt_pk_bf16_f32 v19, v94, v95
	v_cvt_pk_bf16_f32 v20, v96, v97
	v_cvt_pk_bf16_f32 v21, v98, v99
	s_cmpk_eq_i32 s27, 0x380
	s_cbranch_scc1 .Lmy_b2_w0
	s_waitcnt vmcnt(8)
	s_branch .Lmy_b2_w1

; #define MFMA16(a, b, c) __builtin_amdgcn_mfma_f32_16x16x32_bf16((a), (b), (c), 0, 0, 0)
; DI void phaseB2(const Params& p0, int layer, unsigned char* lds) {
;     ...
; #pragma unroll
;       for (int dt = 0; dt < 4; ++dt) {
;         const bf16x8 wf = ld8(W2 + (long)(dt * 16 + qi) * 256 + ksx * 32 + quad * 8);
;         o[dt] = kv ? MFMA16(hf, wf, o[dt]) : MFMA16(wf, hf, o[dt]);
;       }
.Lmy_b2_w1:
	s_cmp_lg_u64 s[8:9], 0
	s_cbranch_scc0 .Lmy_b2_k
	v_mfma_f32_16x16x32_bf16 v[14:17], v[18:21], v[100:103], v[14:17]
	v_mfma_f32_16x16x32_bf16 v[10:13], v[18:21], v[104:107], v[10:13]
	v_mfma_f32_16x16x32_bf16 v[6:9], v[18:21], v[108:111], v[6:9]
	v_mfma_f32_16x16x32_bf16 v[2:5], v[18:21], v[112:115], v[2:5]
	s_branch .Lmy_b2_next

; #define MFMA16(a, b, c) __builtin_amdgcn_mfma_f32_16x16x32_bf16((a), (b), (c), 0, 0, 0)
; DI unsigned pk2(float lo, float hi) { f32x2 v = {lo, hi}; bf16x2_t b = __builtin_convertvector(v, bf16x2_t); return __builtin_bit_cast(unsigned, b); }
; DI float siluf_(float x) { return x * __builtin_amdgcn_rcpf(1.f + __builtin_amdgcn_exp2f(-1.44269504089f * x)); }
; DI void phaseB2(const Params& p0, int layer, unsigned char* lds) {
;     ...
;     for (int ksx = 0; ksx < 8; ++ksx) {
;       f32x4 h0 = *(const f32x4*)(bias_s + kv * 256 + ksx * 32 + quad * 8), h1 = *(const f32x4*)(bias_s + kv * 256 + ksx * 32 + quad * 8 + 4);
; #pragma unroll
;       for (int sp = 0; sp < 4; ++sp) { const float* q = hp + (long)sp * 32 * 256 * 256 + ksx * 32; h0 += *(const f32x4*)q; h1 += *(const f32x4*)(q + 4); }
;       const bf16x8 hf = mk8((u32x4){pk2(siluf_(h0[0]), siluf_(h0[1])), pk2(siluf_(h0[2]), siluf_(h0[3])), pk2(siluf_(h1[0]), siluf_(h1[1])), pk2(siluf_(h1[2]), siluf_(h1[3]))});
; #pragma unroll
;       for (int dt = 0; dt < 4; ++dt) {
;         const bf16x8 wf = ld8(W2 + (long)(dt * 16 + qi) * 256 + ksx * 32 + quad * 8);
;         o[dt] = kv ? MFMA16(hf, wf, o[dt]) : MFMA16(wf, hf, o[dt]);
;       }
.Lmy_b2_next:
	s_cmpk_eq_i32 s27, 0x380
	s_cbranch_scc1 .Lmy_b2_nopf
	v_lshl_add_u64 v[42:43], v[40:41], 0, s[4:5]
	s_mov_b64 s[28:29], 0xec0040
	v_lshl_add_u64 v[56:57], v[42:43], 0, s[28:29]
	global_load_dwordx4 v[100:103], v[56:57], off
	s_mov_b64 s[28:29], 0xec2040
	v_lshl_add_u64 v[56:57], v[42:43], 0, s[28:29]
	global_load_dwordx4 v[104:107], v[56:57], off
	s_mov_b64 s[28:29], 0xec4040
	v_lshl_add_u64 v[56:57], v[42:43], 0, s[28:29]
	global_load_dwordx4 v[108:111], v[56:57], off
	s_mov_b64 s[28:29], 0xec6040
	v_lshl_add_u64 v[56:57], v[42:43], 0, s[28:29]
	global_load_dwordx4 v[112:115], v[56:57], off
